# ssm_pass0 block loop hand-written: 8 MFMAs into distinct quads, batched ds_write/ds_read, scalar 6-op complex scan step
# speedup vs baseline: 1.0108x; 1.0041x over previous
.LBB0_791:
	s_add_i32 s3, s2, -3
	s_min_i32 s4, s3, 0x80
	s_lshl_b32 s4, s4, 4
	s_add_i32 s4, s4, s34
	v_or_b32_e32 v8, s4, v37
	s_add_i32 s4, s2, -2
	s_min_i32 s4, s4, 0x80
	s_lshl_b32 s4, s4, 4
	v_ashrrev_i32_e32 v9, 31, v8
	s_add_i32 s4, s4, s34
	v_lshlrev_b64 v[8:9], 10, v[8:9]
	s_cmp_lg_u32 s2, 2
	v_lshl_add_u64 v[8:9], v[62:63], 0, v[8:9]
	s_cselect_b32 s4, s4, 0x8000
	global_load_dwordx2 v[70:71], v[8:9], off
	v_or_b32_e32 v8, s4, v37
	v_ashrrev_i32_e32 v9, 31, v8
	v_lshlrev_b64 v[8:9], 10, v[8:9]
	v_lshl_add_u64 v[8:9], v[62:63], 0, v[8:9]
	global_load_dwordx2 v[74:75], v[8:9], off
	v_sub_co_u32_e64 v8, s[40:41], s2, 1
	v_min_i32_e32 v8, 0x80, v8
	v_lshlrev_b32_e32 v8, 4, v8
	v_add_u32_e32 v8, s34, v8
	s_min_i32 s4, s2, 0x80
	v_or_b32_e32 v8, v8, v37
	s_lshl_b32 s4, s4, 4
	v_ashrrev_i32_e32 v9, 31, v8
	s_add_i32 s4, s4, s34
	v_lshlrev_b64 v[8:9], 10, v[8:9]
	s_and_b64 s[40:41], s[40:41], exec
	v_lshl_add_u64 v[8:9], v[62:63], 0, v[8:9]
	s_cselect_b32 s4, 0x8000, s4
	global_load_dwordx2 v[76:77], v[8:9], off
	v_or_b32_e32 v8, s4, v37
	v_ashrrev_i32_e32 v9, 31, v8
	v_lshlrev_b64 v[8:9], 10, v[8:9]
	v_lshl_add_u64 v[8:9], v[62:63], 0, v[8:9]
	global_load_dwordx2 v[78:79], v[8:9], off
	s_waitcnt vmcnt(4)
	v_mfma_f32_16x16x16_bf16 v[112:115], v[26:27], v[6:7], 0
	v_mfma_f32_16x16x16_bf16 v[116:119], v[28:29], v[6:7], 0
	v_mfma_f32_16x16x16_bf16 v[120:123], v[30:31], v[6:7], 0
	v_mfma_f32_16x16x16_bf16 v[124:127], v[52:53], v[6:7], 0
	v_mfma_f32_16x16x16_bf16 v[128:131], v[54:55], v[6:7], 0
	v_mfma_f32_16x16x16_bf16 v[132:135], v[56:57], v[6:7], 0
	v_mfma_f32_16x16x16_bf16 v[136:139], v[58:59], v[6:7], 0
	v_mfma_f32_16x16x16_bf16 v[140:143], v[60:61], v[6:7], 0
	s_nop 7
	ds_write_b32 v41, v112
	ds_write_b32 v41, v113 offset:144
	ds_write_b32 v41, v114 offset:288
	ds_write_b32 v85, v115
	ds_write_b32 v41, v116 offset:64
	ds_write_b32 v41, v117 offset:208
	ds_write_b32 v41, v118 offset:352
	ds_write_b32 v85, v119 offset:64
	ds_write_b32 v41, v120 offset:2304
	ds_write_b32 v41, v121 offset:2448
	ds_write_b32 v41, v122 offset:2592
	ds_write_b32 v86, v123
	ds_write_b32 v41, v124 offset:2368
	ds_write_b32 v41, v125 offset:2512
	ds_write_b32 v41, v126 offset:2656
	ds_write_b32 v86, v127 offset:64
	ds_write_b32 v41, v128 offset:4608
	ds_write_b32 v41, v129 offset:4752
	ds_write_b32 v41, v130 offset:4896
	ds_write_b32 v87, v131
	ds_write_b32 v41, v132 offset:4672
	ds_write_b32 v41, v133 offset:4816
	ds_write_b32 v41, v134 offset:4960
	ds_write_b32 v87, v135 offset:64
	ds_write_b32 v41, v136 offset:6912
	ds_write_b32 v41, v137 offset:7056
	ds_write_b32 v41, v138 offset:7200
	ds_write_b32 v88, v139
	ds_write_b32 v41, v140 offset:6976
	ds_write_b32 v41, v141 offset:7120
	ds_write_b32 v41, v142 offset:7264
	ds_write_b32 v88, v143 offset:64
	s_waitcnt lgkmcnt(0)
	ds_read_b128 v[206:209], v89
	ds_read_b128 v[210:213], v89 offset:16
	ds_read_b128 v[214:217], v89 offset:32
	ds_read_b128 v[218:221], v89 offset:48
	ds_read_b128 v[222:225], v89 offset:64
	ds_read_b128 v[226:229], v89 offset:80
	ds_read_b128 v[230:233], v89 offset:96
	ds_read_b128 v[234:237], v89 offset:112
	s_waitcnt lgkmcnt(3)
	v_mul_f32_e32 v204, v48, v0
	v_mul_f32_e32 v205, v48, v1
	v_fma_f32 v204, v50, v1, -v204
	v_fma_f32 v205, v50, v0, v205
	v_add_f32_e32 v1, v206, v204
	v_add_f32_e32 v0, v222, v205
	v_mul_f32_e32 v204, v48, v0
	v_mul_f32_e32 v205, v48, v1
	v_fma_f32 v204, v50, v1, -v204
	v_fma_f32 v205, v50, v0, v205
	v_add_f32_e32 v1, v207, v204
	v_add_f32_e32 v0, v223, v205
	v_mul_f32_e32 v204, v48, v0
	v_mul_f32_e32 v205, v48, v1
	v_fma_f32 v204, v50, v1, -v204
	v_fma_f32 v205, v50, v0, v205
	v_add_f32_e32 v1, v208, v204
	v_add_f32_e32 v0, v224, v205
	v_mul_f32_e32 v204, v48, v0
	v_mul_f32_e32 v205, v48, v1
	v_fma_f32 v204, v50, v1, -v204
	v_fma_f32 v205, v50, v0, v205
	v_add_f32_e32 v1, v209, v204
	v_add_f32_e32 v0, v225, v205
	s_waitcnt lgkmcnt(2)
	v_mul_f32_e32 v204, v48, v0
	v_mul_f32_e32 v205, v48, v1
	v_fma_f32 v204, v50, v1, -v204
	v_fma_f32 v205, v50, v0, v205
	v_add_f32_e32 v1, v210, v204
	v_add_f32_e32 v0, v226, v205
	v_mul_f32_e32 v204, v48, v0
	v_mul_f32_e32 v205, v48, v1
	v_fma_f32 v204, v50, v1, -v204
	v_fma_f32 v205, v50, v0, v205
	v_add_f32_e32 v1, v211, v204
	v_add_f32_e32 v0, v227, v205
	v_mul_f32_e32 v204, v48, v0
	v_mul_f32_e32 v205, v48, v1
	v_fma_f32 v204, v50, v1, -v204
	v_fma_f32 v205, v50, v0, v205
	v_add_f32_e32 v1, v212, v204
	v_add_f32_e32 v0, v228, v205
	v_mul_f32_e32 v204, v48, v0
	v_mul_f32_e32 v205, v48, v1
	v_fma_f32 v204, v50, v1, -v204
	v_fma_f32 v205, v50, v0, v205
	v_add_f32_e32 v1, v213, v204
	v_add_f32_e32 v0, v229, v205
	s_waitcnt lgkmcnt(1)
	v_mul_f32_e32 v204, v48, v0
	v_mul_f32_e32 v205, v48, v1
	v_fma_f32 v204, v50, v1, -v204
	v_fma_f32 v205, v50, v0, v205
	v_add_f32_e32 v1, v214, v204
	v_add_f32_e32 v0, v230, v205
	v_mul_f32_e32 v204, v48, v0
	v_mul_f32_e32 v205, v48, v1
	v_fma_f32 v204, v50, v1, -v204
	v_fma_f32 v205, v50, v0, v205
	v_add_f32_e32 v1, v215, v204
	v_add_f32_e32 v0, v231, v205
	v_mul_f32_e32 v204, v48, v0
	v_mul_f32_e32 v205, v48, v1
	v_fma_f32 v204, v50, v1, -v204
	v_fma_f32 v205, v50, v0, v205
	v_add_f32_e32 v1, v216, v204
	v_add_f32_e32 v0, v232, v205
	v_mul_f32_e32 v204, v48, v0
	v_mul_f32_e32 v205, v48, v1
	v_fma_f32 v204, v50, v1, -v204
	v_fma_f32 v205, v50, v0, v205
	v_add_f32_e32 v1, v217, v204
	v_add_f32_e32 v0, v233, v205
	s_waitcnt lgkmcnt(0)
	v_mul_f32_e32 v204, v48, v0
	v_mul_f32_e32 v205, v48, v1
	v_fma_f32 v204, v50, v1, -v204
	v_fma_f32 v205, v50, v0, v205
	v_add_f32_e32 v1, v218, v204
	v_add_f32_e32 v0, v234, v205
	v_mul_f32_e32 v204, v48, v0
	v_mul_f32_e32 v205, v48, v1
	v_fma_f32 v204, v50, v1, -v204
	v_fma_f32 v205, v50, v0, v205
	v_add_f32_e32 v1, v219, v204
	v_add_f32_e32 v0, v235, v205
	v_mul_f32_e32 v204, v48, v0
	v_mul_f32_e32 v205, v48, v1
	v_fma_f32 v204, v50, v1, -v204
	v_fma_f32 v205, v50, v0, v205
	v_add_f32_e32 v1, v220, v204
	v_add_f32_e32 v0, v236, v205
	v_mul_f32_e32 v204, v48, v0
	v_mul_f32_e32 v205, v48, v1
	v_fma_f32 v204, v50, v1, -v204
	v_fma_f32 v205, v50, v0, v205
	v_add_f32_e32 v1, v221, v204
	v_add_f32_e32 v0, v237, v205
	v_mfma_f32_16x16x16_bf16 v[112:115], v[26:27], v[2:3], 0
	v_mfma_f32_16x16x16_bf16 v[116:119], v[28:29], v[2:3], 0
	v_mfma_f32_16x16x16_bf16 v[120:123], v[30:31], v[2:3], 0
	v_mfma_f32_16x16x16_bf16 v[124:127], v[52:53], v[2:3], 0
	v_mfma_f32_16x16x16_bf16 v[128:131], v[54:55], v[2:3], 0
	v_mfma_f32_16x16x16_bf16 v[132:135], v[56:57], v[2:3], 0
	v_mfma_f32_16x16x16_bf16 v[136:139], v[58:59], v[2:3], 0
	v_mfma_f32_16x16x16_bf16 v[140:143], v[60:61], v[2:3], 0
	s_nop 7
	ds_write_b32 v41, v112
	ds_write_b32 v41, v113 offset:144
	ds_write_b32 v41, v114 offset:288
	ds_write_b32 v85, v115
	ds_write_b32 v41, v116 offset:64
	ds_write_b32 v41, v117 offset:208
	ds_write_b32 v41, v118 offset:352
	ds_write_b32 v85, v119 offset:64
	ds_write_b32 v41, v120 offset:2304
	ds_write_b32 v41, v121 offset:2448
	ds_write_b32 v41, v122 offset:2592
	ds_write_b32 v86, v123
	ds_write_b32 v41, v124 offset:2368
	ds_write_b32 v41, v125 offset:2512
	ds_write_b32 v41, v126 offset:2656
	ds_write_b32 v86, v127 offset:64
	ds_write_b32 v41, v128 offset:4608
	ds_write_b32 v41, v129 offset:4752
	ds_write_b32 v41, v130 offset:4896
	ds_write_b32 v87, v131
	ds_write_b32 v41, v132 offset:4672
	ds_write_b32 v41, v133 offset:4816
	ds_write_b32 v41, v134 offset:4960
	ds_write_b32 v87, v135 offset:64
	ds_write_b32 v41, v136 offset:6912
	ds_write_b32 v41, v137 offset:7056
	ds_write_b32 v41, v138 offset:7200
	ds_write_b32 v88, v139
	ds_write_b32 v41, v140 offset:6976
	ds_write_b32 v41, v141 offset:7120
	ds_write_b32 v41, v142 offset:7264
	ds_write_b32 v88, v143 offset:64
	s_waitcnt lgkmcnt(0)
	ds_read_b128 v[206:209], v89
	ds_read_b128 v[210:213], v89 offset:16
	ds_read_b128 v[214:217], v89 offset:32
	ds_read_b128 v[218:221], v89 offset:48
	ds_read_b128 v[222:225], v89 offset:64
	ds_read_b128 v[226:229], v89 offset:80
	ds_read_b128 v[230:233], v89 offset:96
	ds_read_b128 v[234:237], v89 offset:112
	s_waitcnt lgkmcnt(3)
	v_mul_f32_e32 v204, v48, v0
	v_mul_f32_e32 v205, v48, v1
	v_fma_f32 v204, v50, v1, -v204
	v_fma_f32 v205, v50, v0, v205
	v_add_f32_e32 v1, v206, v204
	v_add_f32_e32 v0, v222, v205
	v_mul_f32_e32 v204, v48, v0
	v_mul_f32_e32 v205, v48, v1
	v_fma_f32 v204, v50, v1, -v204
	v_fma_f32 v205, v50, v0, v205
	v_add_f32_e32 v1, v207, v204
	v_add_f32_e32 v0, v223, v205
	v_mul_f32_e32 v204, v48, v0
	v_mul_f32_e32 v205, v48, v1
	v_fma_f32 v204, v50, v1, -v204
	v_fma_f32 v205, v50, v0, v205
	v_add_f32_e32 v1, v208, v204
	v_add_f32_e32 v0, v224, v205
	v_mul_f32_e32 v204, v48, v0
	v_mul_f32_e32 v205, v48, v1
	v_fma_f32 v204, v50, v1, -v204
	v_fma_f32 v205, v50, v0, v205
	v_add_f32_e32 v1, v209, v204
	v_add_f32_e32 v0, v225, v205
	s_waitcnt lgkmcnt(2)
	v_mul_f32_e32 v204, v48, v0
	v_mul_f32_e32 v205, v48, v1
	v_fma_f32 v204, v50, v1, -v204
	v_fma_f32 v205, v50, v0, v205
	v_add_f32_e32 v1, v210, v204
	v_add_f32_e32 v0, v226, v205
	v_mul_f32_e32 v204, v48, v0
	v_mul_f32_e32 v205, v48, v1
	v_fma_f32 v204, v50, v1, -v204
	v_fma_f32 v205, v50, v0, v205
	v_add_f32_e32 v1, v211, v204
	v_add_f32_e32 v0, v227, v205
	v_mul_f32_e32 v204, v48, v0
	v_mul_f32_e32 v205, v48, v1
	v_fma_f32 v204, v50, v1, -v204
	v_fma_f32 v205, v50, v0, v205
	v_add_f32_e32 v1, v212, v204
	v_add_f32_e32 v0, v228, v205
	v_mul_f32_e32 v204, v48, v0
	v_mul_f32_e32 v205, v48, v1
	v_fma_f32 v204, v50, v1, -v204
	v_fma_f32 v205, v50, v0, v205
	v_add_f32_e32 v1, v213, v204
	v_add_f32_e32 v0, v229, v205
	s_waitcnt lgkmcnt(1)
	v_mul_f32_e32 v204, v48, v0
	v_mul_f32_e32 v205, v48, v1
	v_fma_f32 v204, v50, v1, -v204
	v_fma_f32 v205, v50, v0, v205
	v_add_f32_e32 v1, v214, v204
	v_add_f32_e32 v0, v230, v205
	v_mul_f32_e32 v204, v48, v0
	v_mul_f32_e32 v205, v48, v1
	v_fma_f32 v204, v50, v1, -v204
	v_fma_f32 v205, v50, v0, v205
	v_add_f32_e32 v1, v215, v204
	v_add_f32_e32 v0, v231, v205
	v_mul_f32_e32 v204, v48, v0
	v_mul_f32_e32 v205, v48, v1
	v_fma_f32 v204, v50, v1, -v204
	v_fma_f32 v205, v50, v0, v205
	v_add_f32_e32 v1, v216, v204
	v_add_f32_e32 v0, v232, v205
	v_mul_f32_e32 v204, v48, v0
	v_mul_f32_e32 v205, v48, v1
	v_fma_f32 v204, v50, v1, -v204
	v_fma_f32 v205, v50, v0, v205
	v_add_f32_e32 v1, v217, v204
	v_add_f32_e32 v0, v233, v205
	s_waitcnt lgkmcnt(0)
	v_mul_f32_e32 v204, v48, v0
	v_mul_f32_e32 v205, v48, v1
	v_fma_f32 v204, v50, v1, -v204
	v_fma_f32 v205, v50, v0, v205
	v_add_f32_e32 v1, v218, v204
	v_add_f32_e32 v0, v234, v205
	v_mul_f32_e32 v204, v48, v0
	v_mul_f32_e32 v205, v48, v1
	v_fma_f32 v204, v50, v1, -v204
	v_fma_f32 v205, v50, v0, v205
	v_add_f32_e32 v1, v219, v204
	v_add_f32_e32 v0, v235, v205
	v_mul_f32_e32 v204, v48, v0
	v_mul_f32_e32 v205, v48, v1
	v_fma_f32 v204, v50, v1, -v204
	v_fma_f32 v205, v50, v0, v205
	v_add_f32_e32 v1, v220, v204
	v_add_f32_e32 v0, v236, v205
	v_mul_f32_e32 v204, v48, v0
	v_mul_f32_e32 v205, v48, v1
	v_fma_f32 v204, v50, v1, -v204
	v_fma_f32 v205, v50, v0, v205
	v_add_f32_e32 v1, v221, v204
	v_add_f32_e32 v0, v237, v205
	v_mfma_f32_16x16x16_bf16 v[112:115], v[26:27], v[4:5], 0
	v_mfma_f32_16x16x16_bf16 v[116:119], v[28:29], v[4:5], 0
	v_mfma_f32_16x16x16_bf16 v[120:123], v[30:31], v[4:5], 0
	v_mfma_f32_16x16x16_bf16 v[124:127], v[52:53], v[4:5], 0
	v_mfma_f32_16x16x16_bf16 v[128:131], v[54:55], v[4:5], 0
	v_mfma_f32_16x16x16_bf16 v[132:135], v[56:57], v[4:5], 0
	v_mfma_f32_16x16x16_bf16 v[136:139], v[58:59], v[4:5], 0
	v_mfma_f32_16x16x16_bf16 v[140:143], v[60:61], v[4:5], 0
	s_nop 7
	ds_write_b32 v41, v112
	ds_write_b32 v41, v113 offset:144
	ds_write_b32 v41, v114 offset:288
	ds_write_b32 v85, v115
	ds_write_b32 v41, v116 offset:64
	ds_write_b32 v41, v117 offset:208
	ds_write_b32 v41, v118 offset:352
	ds_write_b32 v85, v119 offset:64
	ds_write_b32 v41, v120 offset:2304
	ds_write_b32 v41, v121 offset:2448
	ds_write_b32 v41, v122 offset:2592
	ds_write_b32 v86, v123
	ds_write_b32 v41, v124 offset:2368
	ds_write_b32 v41, v125 offset:2512
	ds_write_b32 v41, v126 offset:2656
	ds_write_b32 v86, v127 offset:64
	ds_write_b32 v41, v128 offset:4608
	ds_write_b32 v41, v129 offset:4752
	ds_write_b32 v41, v130 offset:4896
	ds_write_b32 v87, v131
	ds_write_b32 v41, v132 offset:4672
	ds_write_b32 v41, v133 offset:4816
	ds_write_b32 v41, v134 offset:4960
	ds_write_b32 v87, v135 offset:64
	ds_write_b32 v41, v136 offset:6912
	ds_write_b32 v41, v137 offset:7056
	ds_write_b32 v41, v138 offset:7200
	ds_write_b32 v88, v139
	ds_write_b32 v41, v140 offset:6976
	ds_write_b32 v41, v141 offset:7120
	ds_write_b32 v41, v142 offset:7264
	ds_write_b32 v88, v143 offset:64
	s_waitcnt lgkmcnt(0)
	ds_read_b128 v[206:209], v89
	ds_read_b128 v[210:213], v89 offset:16
	ds_read_b128 v[214:217], v89 offset:32
	ds_read_b128 v[218:221], v89 offset:48
	ds_read_b128 v[222:225], v89 offset:64
	ds_read_b128 v[226:229], v89 offset:80
	ds_read_b128 v[230:233], v89 offset:96
	ds_read_b128 v[234:237], v89 offset:112
	s_waitcnt lgkmcnt(3)
	v_mul_f32_e32 v204, v48, v0
	v_mul_f32_e32 v205, v48, v1
	v_fma_f32 v204, v50, v1, -v204
	v_fma_f32 v205, v50, v0, v205
	v_add_f32_e32 v1, v206, v204
	v_add_f32_e32 v0, v222, v205
	v_mul_f32_e32 v204, v48, v0
	v_mul_f32_e32 v205, v48, v1
	v_fma_f32 v204, v50, v1, -v204
	v_fma_f32 v205, v50, v0, v205
	v_add_f32_e32 v1, v207, v204
	v_add_f32_e32 v0, v223, v205
	v_mul_f32_e32 v204, v48, v0
	v_mul_f32_e32 v205, v48, v1
	v_fma_f32 v204, v50, v1, -v204
	v_fma_f32 v205, v50, v0, v205
	v_add_f32_e32 v1, v208, v204
	v_add_f32_e32 v0, v224, v205
	v_mul_f32_e32 v204, v48, v0
	v_mul_f32_e32 v205, v48, v1
	v_fma_f32 v204, v50, v1, -v204
	v_fma_f32 v205, v50, v0, v205
	v_add_f32_e32 v1, v209, v204
	v_add_f32_e32 v0, v225, v205
	s_waitcnt lgkmcnt(2)
	v_mul_f32_e32 v204, v48, v0
	v_mul_f32_e32 v205, v48, v1
	v_fma_f32 v204, v50, v1, -v204
	v_fma_f32 v205, v50, v0, v205
	v_add_f32_e32 v1, v210, v204
	v_add_f32_e32 v0, v226, v205
	v_mul_f32_e32 v204, v48, v0
	v_mul_f32_e32 v205, v48, v1
	v_fma_f32 v204, v50, v1, -v204
	v_fma_f32 v205, v50, v0, v205
	v_add_f32_e32 v1, v211, v204
	v_add_f32_e32 v0, v227, v205
	v_mul_f32_e32 v204, v48, v0
	v_mul_f32_e32 v205, v48, v1
	v_fma_f32 v204, v50, v1, -v204
	v_fma_f32 v205, v50, v0, v205
	v_add_f32_e32 v1, v212, v204
	v_add_f32_e32 v0, v228, v205
	v_mul_f32_e32 v204, v48, v0
	v_mul_f32_e32 v205, v48, v1
	v_fma_f32 v204, v50, v1, -v204
	v_fma_f32 v205, v50, v0, v205
	v_add_f32_e32 v1, v213, v204
	v_add_f32_e32 v0, v229, v205
	s_waitcnt lgkmcnt(1)
	v_mul_f32_e32 v204, v48, v0
	v_mul_f32_e32 v205, v48, v1
	v_fma_f32 v204, v50, v1, -v204
	v_fma_f32 v205, v50, v0, v205
	v_add_f32_e32 v1, v214, v204
	v_add_f32_e32 v0, v230, v205
	v_mul_f32_e32 v204, v48, v0
	v_mul_f32_e32 v205, v48, v1
	v_fma_f32 v204, v50, v1, -v204
	v_fma_f32 v205, v50, v0, v205
	v_add_f32_e32 v1, v215, v204
	v_add_f32_e32 v0, v231, v205
	v_mul_f32_e32 v204, v48, v0
	v_mul_f32_e32 v205, v48, v1
	v_fma_f32 v204, v50, v1, -v204
	v_fma_f32 v205, v50, v0, v205
	v_add_f32_e32 v1, v216, v204
	v_add_f32_e32 v0, v232, v205
	v_mul_f32_e32 v204, v48, v0
	v_mul_f32_e32 v205, v48, v1
	v_fma_f32 v204, v50, v1, -v204
	v_fma_f32 v205, v50, v0, v205
	v_add_f32_e32 v1, v217, v204
	v_add_f32_e32 v0, v233, v205
	s_waitcnt lgkmcnt(0)
	v_mul_f32_e32 v204, v48, v0
	v_mul_f32_e32 v205, v48, v1
	v_fma_f32 v204, v50, v1, -v204
	v_fma_f32 v205, v50, v0, v205
	v_add_f32_e32 v1, v218, v204
	v_add_f32_e32 v0, v234, v205
	v_mul_f32_e32 v204, v48, v0
	v_mul_f32_e32 v205, v48, v1
	v_fma_f32 v204, v50, v1, -v204
	v_fma_f32 v205, v50, v0, v205
	v_add_f32_e32 v1, v219, v204
	v_add_f32_e32 v0, v235, v205
	v_mul_f32_e32 v204, v48, v0
	v_mul_f32_e32 v205, v48, v1
	v_fma_f32 v204, v50, v1, -v204
	v_fma_f32 v205, v50, v0, v205
	v_add_f32_e32 v1, v220, v204
	v_add_f32_e32 v0, v236, v205
	v_mul_f32_e32 v204, v48, v0
	v_mul_f32_e32 v205, v48, v1
	v_fma_f32 v204, v50, v1, -v204
	v_fma_f32 v205, v50, v0, v205
	v_add_f32_e32 v1, v221, v204
	v_add_f32_e32 v0, v237, v205
	v_mfma_f32_16x16x16_bf16 v[112:115], v[26:27], v[68:69], 0
	v_mfma_f32_16x16x16_bf16 v[116:119], v[28:29], v[68:69], 0
	v_mfma_f32_16x16x16_bf16 v[120:123], v[30:31], v[68:69], 0
	v_mfma_f32_16x16x16_bf16 v[124:127], v[52:53], v[68:69], 0
	v_mfma_f32_16x16x16_bf16 v[128:131], v[54:55], v[68:69], 0
	v_mfma_f32_16x16x16_bf16 v[132:135], v[56:57], v[68:69], 0
	v_mfma_f32_16x16x16_bf16 v[136:139], v[58:59], v[68:69], 0
	v_mfma_f32_16x16x16_bf16 v[140:143], v[60:61], v[68:69], 0
	s_nop 7
	ds_write_b32 v41, v112
	ds_write_b32 v41, v113 offset:144
	ds_write_b32 v41, v114 offset:288
	ds_write_b32 v85, v115
	ds_write_b32 v41, v116 offset:64
	ds_write_b32 v41, v117 offset:208
	ds_write_b32 v41, v118 offset:352
	ds_write_b32 v85, v119 offset:64
	ds_write_b32 v41, v120 offset:2304
	ds_write_b32 v41, v121 offset:2448
	ds_write_b32 v41, v122 offset:2592
	ds_write_b32 v86, v123
	ds_write_b32 v41, v124 offset:2368
	ds_write_b32 v41, v125 offset:2512
	ds_write_b32 v41, v126 offset:2656
	ds_write_b32 v86, v127 offset:64
	ds_write_b32 v41, v128 offset:4608
	ds_write_b32 v41, v129 offset:4752
	ds_write_b32 v41, v130 offset:4896
	ds_write_b32 v87, v131
	ds_write_b32 v41, v132 offset:4672
	ds_write_b32 v41, v133 offset:4816
	ds_write_b32 v41, v134 offset:4960
	ds_write_b32 v87, v135 offset:64
	ds_write_b32 v41, v136 offset:6912
	ds_write_b32 v41, v137 offset:7056
	ds_write_b32 v41, v138 offset:7200
	ds_write_b32 v88, v139
	ds_write_b32 v41, v140 offset:6976
	ds_write_b32 v41, v141 offset:7120
	ds_write_b32 v41, v142 offset:7264
	ds_write_b32 v88, v143 offset:64
	s_waitcnt lgkmcnt(0)
	ds_read_b128 v[206:209], v89
	ds_read_b128 v[210:213], v89 offset:16
	ds_read_b128 v[214:217], v89 offset:32
	ds_read_b128 v[218:221], v89 offset:48
	ds_read_b128 v[222:225], v89 offset:64
	ds_read_b128 v[226:229], v89 offset:80
	ds_read_b128 v[230:233], v89 offset:96
	ds_read_b128 v[234:237], v89 offset:112
	s_waitcnt lgkmcnt(3)
	v_mul_f32_e32 v204, v48, v0
	v_mul_f32_e32 v205, v48, v1
	v_fma_f32 v204, v50, v1, -v204
	v_fma_f32 v205, v50, v0, v205
	v_add_f32_e32 v1, v206, v204
	v_add_f32_e32 v0, v222, v205
	v_mul_f32_e32 v204, v48, v0
	v_mul_f32_e32 v205, v48, v1
	v_fma_f32 v204, v50, v1, -v204
	v_fma_f32 v205, v50, v0, v205
	v_add_f32_e32 v1, v207, v204
	v_add_f32_e32 v0, v223, v205
	v_mul_f32_e32 v204, v48, v0
	v_mul_f32_e32 v205, v48, v1
	v_fma_f32 v204, v50, v1, -v204
	v_fma_f32 v205, v50, v0, v205
	v_add_f32_e32 v1, v208, v204
	v_add_f32_e32 v0, v224, v205
	v_mul_f32_e32 v204, v48, v0
	v_mul_f32_e32 v205, v48, v1
	v_fma_f32 v204, v50, v1, -v204
	v_fma_f32 v205, v50, v0, v205
	v_add_f32_e32 v1, v209, v204
	v_add_f32_e32 v0, v225, v205
	s_waitcnt lgkmcnt(2)
	v_mul_f32_e32 v204, v48, v0
	v_mul_f32_e32 v205, v48, v1
	v_fma_f32 v204, v50, v1, -v204
	v_fma_f32 v205, v50, v0, v205
	v_add_f32_e32 v1, v210, v204
	v_add_f32_e32 v0, v226, v205
	v_mul_f32_e32 v204, v48, v0
	v_mul_f32_e32 v205, v48, v1
	v_fma_f32 v204, v50, v1, -v204
	v_fma_f32 v205, v50, v0, v205
	v_add_f32_e32 v1, v211, v204
	v_add_f32_e32 v0, v227, v205
	v_mul_f32_e32 v204, v48, v0
	v_mul_f32_e32 v205, v48, v1
	v_fma_f32 v204, v50, v1, -v204
	v_fma_f32 v205, v50, v0, v205
	v_add_f32_e32 v1, v212, v204
	v_add_f32_e32 v0, v228, v205
	v_mul_f32_e32 v204, v48, v0
	v_mul_f32_e32 v205, v48, v1
	v_fma_f32 v204, v50, v1, -v204
	v_fma_f32 v205, v50, v0, v205
	v_add_f32_e32 v1, v213, v204
	v_add_f32_e32 v0, v229, v205
	s_waitcnt lgkmcnt(1)
	v_mul_f32_e32 v204, v48, v0
	v_mul_f32_e32 v205, v48, v1
	v_fma_f32 v204, v50, v1, -v204
	v_fma_f32 v205, v50, v0, v205
	v_add_f32_e32 v1, v214, v204
	v_add_f32_e32 v0, v230, v205
	v_mul_f32_e32 v204, v48, v0
	v_mul_f32_e32 v205, v48, v1
	v_fma_f32 v204, v50, v1, -v204
	v_fma_f32 v205, v50, v0, v205
	v_add_f32_e32 v1, v215, v204
	v_add_f32_e32 v0, v231, v205
	v_mul_f32_e32 v204, v48, v0
	v_mul_f32_e32 v205, v48, v1
	v_fma_f32 v204, v50, v1, -v204
	v_fma_f32 v205, v50, v0, v205
	v_add_f32_e32 v1, v216, v204
	v_add_f32_e32 v0, v232, v205
	v_mul_f32_e32 v204, v48, v0
	v_mul_f32_e32 v205, v48, v1
	v_fma_f32 v204, v50, v1, -v204
	v_fma_f32 v205, v50, v0, v205
	v_add_f32_e32 v1, v217, v204
	v_add_f32_e32 v0, v233, v205
	s_waitcnt lgkmcnt(0)
	v_mul_f32_e32 v204, v48, v0
	v_mul_f32_e32 v205, v48, v1
	v_fma_f32 v204, v50, v1, -v204
	v_fma_f32 v205, v50, v0, v205
	v_add_f32_e32 v1, v218, v204
	v_add_f32_e32 v0, v234, v205
	v_mul_f32_e32 v204, v48, v0
	v_mul_f32_e32 v205, v48, v1
	v_fma_f32 v204, v50, v1, -v204
	v_fma_f32 v205, v50, v0, v205
	v_add_f32_e32 v1, v219, v204
	v_add_f32_e32 v0, v235, v205
	v_mul_f32_e32 v204, v48, v0
	v_mul_f32_e32 v205, v48, v1
	v_fma_f32 v204, v50, v1, -v204
	v_fma_f32 v205, v50, v0, v205
	v_add_f32_e32 v1, v220, v204
	v_add_f32_e32 v0, v236, v205
	v_mul_f32_e32 v204, v48, v0
	v_mul_f32_e32 v205, v48, v1
	v_fma_f32 v204, v50, v1, -v204
	v_fma_f32 v205, v50, v0, v205
	v_add_f32_e32 v1, v221, v204
	v_add_f32_e32 v0, v237, v205
	s_waitcnt vmcnt(0)
	v_mov_b32_e32 v6, v70
	v_mov_b32_e32 v7, v71
	v_mov_b32_e32 v2, v74
	v_mov_b32_e32 v3, v75
	v_mov_b32_e32 v4, v76
	v_mov_b32_e32 v5, v77
	v_mov_b32_e32 v68, v78
	v_mov_b32_e32 v69, v79
	s_add_i32 s2, s2, 4
	s_cmp_lt_i32 s3, s1
	s_cbranch_scc1 .LBB0_791
	s_branch .LBB0_774
